# tile-start de-serialisation: G==256 fast path for the static tile order (pn += 8) in in-proj / gate-up, on top of the 64-bit accumulator clear
# speedup vs baseline: 1.0092x; 1.0041x over previous
;     __host__ __device__ bool next(int i, Unit& u) const {
;         const int ii = dual ? (i >> 1) : i; u.part = dual ? (i & 1) : 0;
;         const long L = (long)ii * G + c; if (L >= nwg) return false;
;         int wgid = (int)L; { const int q = nwg / NXCD, r = nwg % NXCD, xcd = wgid % NXCD, off = wgid / NXCD; wgid = (xcd < r ? xcd * (q + 1) : r * (q + 1) + (xcd - r) * q) + off; }
;         const int nig = WGM * nN, gid = wgid / nig, fm = gid * WGM, gsz = (nM - fm) < WGM ? (nM - fm) : WGM;
;         u.pm = fm + ((wgid % nig) % gsz); u.pn = (wgid % nig) / gsz; return true;
;     }
; template <class Epi, class Sched, bool ALIGN_EPI = false, bool SP2 = false>
; __device__ __forceinline__ void gemm_phase(PG8_LAS unsigned char* lds, const Gemm g, const Sched& S, const Epi& E) {
;     ...
;         const bool has_next = S.next(ui + 1, nxt);
.LBB0_162:
	s_add_i32 s53, s53, 1
	s_mul_i32 s17, s53, s97
	s_mul_hi_u32 s23, s53, s3
	s_add_i32 s23, s23, s17
	s_mul_i32 s17, s53, s3
	s_add_u32 s36, s17, s85
	s_addc_u32 s37, s23, s96
	v_cmp_gt_i64_e32 vcc, s[36:37], v[170:171]
	v_cmp_lt_i64_e64 s[38:39], s[36:37], v[168:169]
	s_cbranch_vccnz .LBB0_164
	s_cmpk_lg_u32 s3, 0x100
	s_cbranch_scc1 .Lsched_in_orig
	s_add_i32 s22, s44, 8
	s_mov_b32 s24, s16
	s_branch .LBB0_164
.Lsched_in_orig:
	s_ashr_i32 s17, s36, 31
	s_lshr_b32 s17, s17, 29
	s_add_i32 s17, s36, s17
	s_ashr_i32 s22, s17, 3
	s_and_b32 s17, s17, -8
	s_sub_i32 s17, s36, s17
	s_cmp_lt_i32 s17, 0
	s_movk_i32 s23, 0x79
	s_cselect_b32 s23, s23, 0x78
	s_mul_i32 s17, s17, s23
	s_add_i32 s17, s17, s22
	s_mul_hi_i32 s22, s17, 0x88888889
	s_add_i32 s22, s22, s17
	s_lshr_b32 s23, s22, 31
	s_ashr_i32 s22, s22, 6
	s_add_i32 s22, s22, s23
	s_lshl_b32 s23, s22, 2
	s_sub_i32 s24, 32, s23
	s_min_i32 s24, s24, 4
	s_abs_i32 s25, s24
	v_cvt_f32_u32_e32 v2, s25
	s_sub_i32 s37, 0, s25
	s_mulk_i32 s22, 0x78
	s_sub_i32 s17, s17, s22
	v_rcp_iflag_f32_e32 v2, v2
	s_abs_i32 s22, s17
	s_xor_b32 s36, s17, s24
	s_ashr_i32 s36, s36, 31
	v_mul_f32_e32 v2, 0x4f7ffffe, v2
	v_cvt_u32_f32_e32 v2, v2
	s_nop 0
	v_readfirstlane_b32 s40, v2
	s_mul_i32 s37, s37, s40
	s_mul_hi_u32 s37, s40, s37
	s_add_i32 s40, s40, s37
	s_mul_hi_u32 s37, s22, s40
	s_mul_i32 s40, s37, s25
	s_sub_i32 s22, s22, s40
	s_add_i32 s41, s37, 1
	s_sub_i32 s40, s22, s25
	s_cmp_ge_u32 s22, s25
	s_cselect_b32 s37, s41, s37
	s_cselect_b32 s22, s40, s22
	s_add_i32 s40, s37, 1
	s_cmp_ge_u32 s22, s25
	s_cselect_b32 s22, s40, s37
	s_xor_b32 s22, s22, s36
	s_sub_i32 s22, s22, s36
	s_mul_i32 s24, s22, s24
	s_sub_i32 s17, s17, s24
	s_add_i32 s24, s23, s17

;     __host__ __device__ bool next(int i, Unit& u) const {
;         const int ii = dual ? (i >> 1) : i; u.part = dual ? (i & 1) : 0;
;         const long L = (long)ii * G + c; if (L >= nwg) return false;
;         int wgid = (int)L; { const int q = nwg / NXCD, r = nwg % NXCD, xcd = wgid % NXCD, off = wgid / NXCD; wgid = (xcd < r ? xcd * (q + 1) : r * (q + 1) + (xcd - r) * q) + off; }
;         const int nig = WGM * nN, gid = wgid / nig, fm = gid * WGM, gsz = (nM - fm) < WGM ? (nM - fm) : WGM;
;         u.pm = fm + ((wgid % nig) % gsz); u.pn = (wgid % nig) / gsz; return true;
;     }
; template <class Epi, class Sched, bool ALIGN_EPI = false, bool SP2 = false>
; __device__ __forceinline__ void gemm_phase(PG8_LAS unsigned char* lds, const Gemm g, const Sched& S, const Epi& E) {
;     ...
;         const bool has_next = S.next(ui + 1, nxt);
.LBB0_656:
	s_add_i32 s50, s50, 1
	s_mul_i32 s21, s50, s97
	s_mul_hi_u32 s23, s50, s3
	s_add_i32 s23, s23, s21
	s_mul_i32 s21, s50, s3
	s_add_u32 s24, s21, s85
	s_addc_u32 s25, s23, s96
	v_cmp_gt_i64_e32 vcc, s[24:25], v[178:179]
	v_cmp_lt_i64_e64 s[40:41], s[24:25], v[176:177]
	s_cbranch_vccnz .LBB0_658
	s_cmpk_lg_u32 s3, 0x100
	s_cbranch_scc1 .Lsched_gu_orig
	s_add_i32 s20, s51, 8
	s_mov_b32 s22, s42
	s_branch .LBB0_658
.Lsched_gu_orig:
	s_ashr_i32 s20, s24, 31
	s_lshr_b32 s20, s20, 29
	s_add_i32 s20, s24, s20
	s_ashr_i32 s21, s20, 3
	s_and_b32 s20, s20, -8
	s_sub_i32 s20, s24, s20
	s_cmp_lt_i32 s20, 0
	s_movk_i32 s22, 0xb1
	s_cselect_b32 s22, s22, 0xb0
	s_mul_i32 s20, s20, s22
	s_add_i32 s20, s20, s21
	s_mul_hi_i32 s21, s20, 0x2e8ba2e9
	s_lshr_b32 s22, s21, 31
	s_ashr_i32 s21, s21, 5
	s_add_i32 s21, s21, s22
	s_lshl_b32 s22, s21, 2
	s_sub_i32 s23, 32, s22
	s_min_i32 s23, s23, 4
	s_abs_i32 s24, s23
	v_cvt_f32_u32_e32 v2, s24
	s_sub_i32 s28, 0, s24
	s_mulk_i32 s21, 0xb0
	s_sub_i32 s21, s20, s21
	v_rcp_iflag_f32_e32 v2, v2
	s_abs_i32 s20, s21
	s_xor_b32 s25, s21, s23
	s_ashr_i32 s25, s25, 31
	v_mul_f32_e32 v2, 0x4f7ffffe, v2
	v_cvt_u32_f32_e32 v2, v2
	s_nop 0
	v_readfirstlane_b32 s29, v2
	s_mul_i32 s28, s28, s29
	s_mul_hi_u32 s28, s29, s28
	s_add_i32 s29, s29, s28
	s_mul_hi_u32 s28, s20, s29
	s_mul_i32 s29, s28, s24
	s_sub_i32 s20, s20, s29
	s_add_i32 s36, s28, 1
	s_sub_i32 s29, s20, s24
	s_cmp_ge_u32 s20, s24
	s_cselect_b32 s28, s36, s28
	s_cselect_b32 s20, s29, s20
	s_add_i32 s29, s28, 1
	s_cmp_ge_u32 s20, s24
	s_cselect_b32 s20, s29, s28
	s_xor_b32 s20, s20, s25
	s_sub_i32 s20, s20, s25
	s_mul_i32 s23, s20, s23
	s_sub_i32 s21, s21, s23
	s_add_i32 s22, s22, s21
